# in-proj-window weight conversion stores made write-through (sc1) to keep them out of the XCD L2
# speedup vs baseline: 1.0023x; 1.0023x over previous
; template <int MAP>
; __device__ __forceinline__ void tr_item(const float* __restrict__ W, int K, int N, const float* __restrict__ gain, bf16_t* WT, LAS float* scr, int item, int lane) {
;     const int nblk = (N + 31) / 32, kb = item / nblk, nb = item % nblk, k0 = 64 * kb, n0 = 32 * nb;
;     const int nsrc = n0 + (lane & 31); const bool ok = nsrc < N;
;     float v[32];
; #pragma unroll
;     for (int i = 0; i < 32; ++i) { const int kk = 2 * i + (lane >> 5); v[i] = ok ? __builtin_nontemporal_load(W + (size_t)(k0 + kk) * N + nsrc) : 0.f; }
; #pragma unroll
;     for (int i = 0; i < 32; ++i) { const int kk = 2 * i + (lane >> 5); float x = v[i]; if (gain) x *= gain[k0 + kk]; scr[kk * 33 + (lane & 31)] = x; }
; __device__ __forceinline__ void tr_dispatch(ArgsP a, int l, int r, LAS float* scr, int lane) {
;     ...
;     if (r < TR_IT_IN) { tr_item<1>(a->in[I_W_IN] + (size_t)l * DM * NIN, DM, NIN, a->in[I_NORM_MIX] + l * DM, (bf16_t*)(ws + WS_WIN + l * SZ_WIN), scr, r, lane); return; } r -= TR_IT_IN;
;     if (r < TR_IT_OUT) { tr_item<0>(a->in[I_WOUT] + (size_t)l * DM * DM, DM, DM, nullptr, (bf16_t*)(ws + WS_WOUT + l * SZ_WOUT), scr, r, lane); return; } r -= TR_IT_OUT;
;     if (r < TR_IT_UP) { tr_item<0>(a->in[I_WUP] + (size_t)l * DM * DFF, DM, DFF, a->in[I_NORM_FFN] + l * DM, (bf16_t*)(ws + WS_WUP + l * SZ_WUP), scr, r, lane); return; } r -= TR_IT_UP;
;     if (r < TR_IT_DN) { tr_item<0>(a->in[I_WDN] + (size_t)l * DFF * DM, DFF, DM, nullptr, (bf16_t*)(ws + WS_WDN + l * SZ_WDN), scr, r, lane); return; } r -= TR_IT_DN;
;     if (r < TR_IT_QUP) { tr_item<0>(a->in[I_WQUP] + (size_t)l * 512 * NQUP, 512, NQUP, a->in[I_QAN] + l * 512, (bf16_t*)(ws + WS_WQUP + l * SZ_WQUP), scr, r, lane); return; } r -= TR_IT_QUP;
;     tr_item<0>(a->in[I_WKVUP] + (size_t)l * 256 * NKVUP, 256, NKVUP, a->in[I_KVAN] + l * 256, (bf16_t*)(ws + WS_WKVUP + l * SZ_WKVUP), scr, r, lane);
.LBB0_1466:
	s_add_i32 s19, s28, s30
	s_cmpk_gt_i32 s19, 0x47ff
	s_cbranch_scc1 .LBB0_1465
	s_add_i32 s18, s19, 0x1260
	s_cmp_gt_i32 s19, -1
	s_mov_b64 s[4:5], -1
	s_cbranch_scc0 .LBB0_1489
	s_cmpk_gt_u32 s18, 0x1a5f
	s_cbranch_scc0 .LBB0_1486
	s_cmpk_gt_u32 s18, 0x3a5f
	s_cbranch_scc0 .LBB0_1471
	s_load_dwordx2 s[4:5], s[0:1], 0xb0
	s_add_i32 s2, s19, 0xffffd800
	s_waitcnt lgkmcnt(0)
	s_add_u32 s6, s4, s8
	s_addc_u32 s7, s5, s9
	s_and_b32 s5, s2, 0xffc0
	s_add_i32 s2, s29, 0xfffb0000
	s_and_b32 s4, s2, 0x7e0
	v_or_b32_e32 v0, s4, v32
	v_or_b32_e32 v14, s5, v2
	v_lshlrev_b32_e32 v0, 2, v0
	v_lshl_add_u64 v[12:13], s[6:7], 0, v[0:1]
	v_lshlrev_b32_e32 v0, 13, v14
	v_lshl_add_u64 v[12:13], v[12:13], 0, v[0:1]
	v_add_co_u32_e32 v14, vcc, s86, v12
	global_load_dword v0, v[12:13], off nt
	s_nop 0
	v_addc_co_u32_e32 v15, vcc, 0, v13, vcc
	global_load_dword v16, v[14:15], off nt
	v_add_co_u32_e32 v14, vcc, s74, v12
	s_mov_b32 s2, 0x74000
	s_nop 0
	v_addc_co_u32_e32 v15, vcc, 0, v13, vcc
	global_load_dword v17, v[14:15], off nt
	v_add_co_u32_e32 v14, vcc, s78, v12
	s_lshl_b32 s36, s5, 1
	s_nop 0
	v_addc_co_u32_e32 v15, vcc, 0, v13, vcc
	global_load_dword v18, v[14:15], off nt
	v_add_co_u32_e32 v14, vcc, s17, v12
	s_nop 1
	v_addc_co_u32_e32 v15, vcc, 0, v13, vcc
	global_load_dword v19, v[14:15], off nt
	v_add_co_u32_e32 v14, vcc, s24, v12
	s_nop 1
	v_addc_co_u32_e32 v15, vcc, 0, v13, vcc
	global_load_dword v20, v[14:15], off nt
	v_add_co_u32_e32 v14, vcc, s87, v12
	s_nop 1
	v_addc_co_u32_e32 v15, vcc, 0, v13, vcc
	global_load_dword v21, v[14:15], off nt
	v_add_co_u32_e32 v14, vcc, s69, v12
	s_nop 1
	v_addc_co_u32_e32 v15, vcc, 0, v13, vcc
	global_load_dword v22, v[14:15], off nt
	v_add_co_u32_e32 v14, vcc, s70, v12
	s_nop 1
	v_addc_co_u32_e32 v15, vcc, 0, v13, vcc
	global_load_dword v23, v[14:15], off nt
	v_add_co_u32_e32 v14, vcc, s72, v12
	s_nop 1
	v_addc_co_u32_e32 v15, vcc, 0, v13, vcc
	global_load_dword v24, v[14:15], off nt
	v_add_co_u32_e32 v14, vcc, s33, v12
	s_nop 1
	v_addc_co_u32_e32 v15, vcc, 0, v13, vcc
	global_load_dword v25, v[14:15], off nt
	v_add_co_u32_e32 v14, vcc, s60, v12
	s_nop 1
	v_addc_co_u32_e32 v15, vcc, 0, v13, vcc
	global_load_dword v26, v[14:15], off nt
	v_add_co_u32_e32 v14, vcc, s83, v12
	s_nop 1
	v_addc_co_u32_e32 v15, vcc, 0, v13, vcc
	global_load_dword v27, v[14:15], off nt
	v_add_co_u32_e32 v14, vcc, s35, v12
	s_nop 1
	v_addc_co_u32_e32 v15, vcc, 0, v13, vcc
	global_load_dword v28, v[14:15], off nt
	v_add_co_u32_e32 v14, vcc, s38, v12
	s_nop 1
	v_addc_co_u32_e32 v15, vcc, 0, v13, vcc
	global_load_dword v29, v[14:15], off nt
	v_add_co_u32_e32 v14, vcc, s39, v12
	s_nop 1
	v_addc_co_u32_e32 v15, vcc, 0, v13, vcc
	global_load_dword v30, v[14:15], off nt
	v_add_co_u32_e32 v14, vcc, s40, v12
	s_nop 1
	v_addc_co_u32_e32 v15, vcc, 0, v13, vcc
	global_load_dword v31, v[14:15], off nt
	v_add_co_u32_e32 v14, vcc, s41, v12
	s_nop 1
	v_addc_co_u32_e32 v15, vcc, 0, v13, vcc
	global_load_dword v44, v[14:15], off nt
	v_add_co_u32_e32 v14, vcc, s42, v12
	s_nop 1
	v_addc_co_u32_e32 v15, vcc, 0, v13, vcc
	global_load_dword v45, v[14:15], off nt
	v_add_co_u32_e32 v14, vcc, s43, v12
	s_nop 1
	v_addc_co_u32_e32 v15, vcc, 0, v13, vcc
	global_load_dword v46, v[14:15], off nt
	v_add_co_u32_e32 v14, vcc, s44, v12
	s_nop 1
	v_addc_co_u32_e32 v15, vcc, 0, v13, vcc
	global_load_dword v47, v[14:15], off nt
	v_add_co_u32_e32 v14, vcc, s45, v12
	s_nop 1
	v_addc_co_u32_e32 v15, vcc, 0, v13, vcc
	global_load_dword v48, v[14:15], off nt
	v_add_co_u32_e32 v14, vcc, s46, v12
	s_nop 1
	v_addc_co_u32_e32 v15, vcc, 0, v13, vcc
	global_load_dword v49, v[14:15], off nt
	v_add_co_u32_e32 v14, vcc, s47, v12
	s_nop 1
	v_addc_co_u32_e32 v15, vcc, 0, v13, vcc
	global_load_dword v50, v[14:15], off nt
	v_add_co_u32_e32 v14, vcc, s68, v12
	s_nop 1
	v_addc_co_u32_e32 v15, vcc, 0, v13, vcc
	global_load_dword v51, v[14:15], off nt
	v_add_co_u32_e32 v14, vcc, s48, v12
	s_nop 1
	v_addc_co_u32_e32 v15, vcc, 0, v13, vcc
	global_load_dword v52, v[14:15], off nt
	v_add_co_u32_e32 v14, vcc, s49, v12
	s_nop 1
	v_addc_co_u32_e32 v15, vcc, 0, v13, vcc
	global_load_dword v53, v[14:15], off nt
	v_add_co_u32_e32 v14, vcc, s91, v12
	s_nop 1
	v_addc_co_u32_e32 v15, vcc, 0, v13, vcc
	global_load_dword v54, v[14:15], off nt
	v_add_co_u32_e32 v14, vcc, s56, v12
	s_nop 1
	v_addc_co_u32_e32 v15, vcc, 0, v13, vcc
	global_load_dword v55, v[14:15], off nt
	v_add_co_u32_e32 v14, vcc, s2, v12
	s_mov_b32 s2, 0x78000
	s_nop 0
	v_addc_co_u32_e32 v15, vcc, 0, v13, vcc
	global_load_dword v56, v[14:15], off nt
	v_add_co_u32_e32 v14, vcc, s2, v12
	s_mov_b32 s2, 0x7c000
	s_nop 0
	v_addc_co_u32_e32 v15, vcc, 0, v13, vcc
	v_add_co_u32_e32 v12, vcc, s2, v12
	global_load_dword v14, v[14:15], off nt
	s_nop 0
	v_addc_co_u32_e32 v13, vcc, 0, v13, vcc
	global_load_dword v12, v[12:13], off nt
	v_add_u32_e32 v13, v33, v34
	s_waitcnt vmcnt(30)
; #define LAS __attribute__((address_space(3)))
; __device__ __forceinline__ unsigned cvtpk(float lo, float hi) { const cvt_f32x2 v = {lo, hi}; const cvt_bf16x2 r = __builtin_convertvector(v, cvt_bf16x2); return __builtin_bit_cast(unsigned, r); }
; template <int MAP>
; __device__ __forceinline__ void tr_item(const float* __restrict__ W, int K, int N, const float* __restrict__ gain, bf16_t* WT, LAS float* scr, int item, int lane) {
;     ...
; #pragma unroll
;     for (int i = 0; i < 32; ++i) { const int kk = 2 * i + (lane >> 5); float x = v[i]; if (gain) x *= gain[k0 + kk]; scr[kk * 33 + (lane & 31)] = x; }
;     asm volatile("s_waitcnt lgkmcnt(0)" ::: "memory");
;     const int c = lane & 7;
; #pragma unroll
;     for (int j = 0; j < 4; ++j) {
;         const int nl = (lane >> 3) + 8 * j, n = n0 + nl;
;         const LAS float* s = scr + (8 * c) * 33 + nl;
;         u32x4 o; o.x = cvtpk(s[0 * 33], s[1 * 33]); o.y = cvtpk(s[2 * 33], s[3 * 33]); o.z = cvtpk(s[4 * 33], s[5 * 33]); o.w = cvtpk(s[6 * 33], s[7 * 33]);
;         int dest = n;
;         if (MAP == 1) { if (n >= 3846) dest = n - 6; else if (n >= 3840) dest = C_FF + (n - 3840); }
;         if (n < N) *(u32x4*)(WT + (size_t)dest * K + k0 + 8 * c) = o;
;     }
;     asm volatile("s_waitcnt lgkmcnt(0)" ::: "memory");
	ds_write2_b32 v13, v0, v16 offset1:66
	s_waitcnt vmcnt(28)
	ds_write2_b32 v13, v17, v18 offset0:132 offset1:198
	v_add_u32_e32 v0, 0x400, v13
	s_waitcnt vmcnt(26)
	ds_write2_b32 v0, v19, v20 offset0:8 offset1:74
	s_waitcnt vmcnt(24)
	ds_write2_b32 v0, v21, v22 offset0:140 offset1:206
	v_add_u32_e32 v0, 0x800, v13
	s_waitcnt vmcnt(22)
	ds_write2_b32 v0, v23, v24 offset0:16 offset1:82
	s_waitcnt vmcnt(20)
	ds_write2_b32 v0, v25, v26 offset0:148 offset1:214
	v_add_u32_e32 v0, 0xc00, v13
	s_waitcnt vmcnt(18)
	ds_write2_b32 v0, v27, v28 offset0:24 offset1:90
	s_waitcnt vmcnt(16)
	ds_write2_b32 v0, v29, v30 offset0:156 offset1:222
	v_add_u32_e32 v0, 0x1000, v13
	s_waitcnt vmcnt(14)
	ds_write2_b32 v0, v31, v44 offset0:32 offset1:98
	s_waitcnt vmcnt(12)
	ds_write2_b32 v0, v45, v46 offset0:164 offset1:230
	v_add_u32_e32 v0, 0x1400, v13
	s_waitcnt vmcnt(10)
	ds_write2_b32 v0, v47, v48 offset0:40 offset1:106
	s_waitcnt vmcnt(8)
	ds_write2_b32 v0, v49, v50 offset0:172 offset1:238
	v_add_u32_e32 v0, 0x1800, v13
	s_waitcnt vmcnt(6)
	ds_write2_b32 v0, v51, v52 offset0:48 offset1:114
	s_waitcnt vmcnt(4)
	ds_write2_b32 v0, v53, v54 offset0:180 offset1:246
	v_add_u32_e32 v0, 0x1c00, v13
	s_waitcnt vmcnt(2)
	ds_write2_b32 v0, v55, v56 offset0:56 offset1:122
	s_waitcnt vmcnt(0)
	ds_write2_b32 v0, v14, v12 offset0:188 offset1:254
	s_waitcnt lgkmcnt(0)
	ds_read2_b32 v[20:21], v40 offset0:33 offset1:41
	ds_read2_b32 v[22:23], v40 offset1:8
	ds_read2_b32 v[24:25], v40 offset0:66 offset1:74
	ds_read2_b32 v[26:27], v40 offset0:99 offset1:107
	ds_read2_b32 v[28:29], v40 offset0:132 offset1:140
	ds_read2_b32 v[30:31], v40 offset0:165 offset1:173
	ds_read2_b32 v[44:45], v40 offset0:198 offset1:206
	ds_read2_b32 v[46:47], v40 offset0:231 offset1:239
	v_or_b32_e32 v0, s4, v39
	v_lshl_add_u64 v[16:17], v[6:7], 0, s[36:37]
	v_lshlrev_b32_e32 v0, 14, v0
	v_lshl_add_u64 v[18:19], v[16:17], 0, v[0:1]
	v_or_b32_e32 v0, s4, v41
	s_waitcnt lgkmcnt(6)
	v_cvt_pk_bf16_f32 v12, v22, v20
	s_waitcnt lgkmcnt(4)
	v_cvt_pk_bf16_f32 v13, v24, v26
	s_waitcnt lgkmcnt(2)
	v_cvt_pk_bf16_f32 v14, v28, v30
	s_waitcnt lgkmcnt(0)
	v_cvt_pk_bf16_f32 v15, v44, v46
	v_lshlrev_b32_e32 v0, 14, v0
	global_store_dwordx4 v[18:19], v[12:15], off sc1
	v_lshl_add_u64 v[18:19], v[16:17], 0, v[0:1]
	v_or_b32_e32 v0, s4, v42
	v_cvt_pk_bf16_f32 v12, v23, v21
	v_cvt_pk_bf16_f32 v13, v25, v27
	v_cvt_pk_bf16_f32 v14, v29, v31
	v_cvt_pk_bf16_f32 v15, v45, v47
	global_store_dwordx4 v[18:19], v[12:15], off sc1
	ds_read2_b32 v[20:21], v40 offset0:49 offset1:57
	ds_read2_b32 v[22:23], v40 offset0:16 offset1:24
	ds_read2_b32 v[24:25], v40 offset0:82 offset1:90
	ds_read2_b32 v[26:27], v40 offset0:115 offset1:123
	ds_read2_b32 v[28:29], v40 offset0:148 offset1:156
	ds_read2_b32 v[30:31], v40 offset0:181 offset1:189
	ds_read2_b32 v[44:45], v40 offset0:214 offset1:222
	ds_read2_b32 v[46:47], v40 offset0:247 offset1:255
	v_lshlrev_b32_e32 v0, 14, v0
	v_lshl_add_u64 v[18:19], v[16:17], 0, v[0:1]
	v_or_b32_e32 v0, s4, v43
	s_waitcnt lgkmcnt(6)
	v_cvt_pk_bf16_f32 v12, v22, v20
	s_waitcnt lgkmcnt(4)
	v_cvt_pk_bf16_f32 v13, v24, v26
	s_waitcnt lgkmcnt(2)
	v_cvt_pk_bf16_f32 v14, v28, v30
	s_waitcnt lgkmcnt(0)
	v_cvt_pk_bf16_f32 v15, v44, v46
	v_lshlrev_b32_e32 v0, 14, v0
	global_store_dwordx4 v[18:19], v[12:15], off sc1
	v_lshl_add_u64 v[16:17], v[16:17], 0, v[0:1]
	s_mov_b64 s[4:5], 0
	v_cvt_pk_bf16_f32 v12, v23, v21
	v_cvt_pk_bf16_f32 v13, v25, v27
	v_cvt_pk_bf16_f32 v14, v29, v31
	v_cvt_pk_bf16_f32 v15, v45, v47
	global_store_dwordx4 v[16:17], v[12:15], off sc1
	s_waitcnt lgkmcnt(0)

; #define LAS __attribute__((address_space(3)))
; __device__ __forceinline__ unsigned cvtpk(float lo, float hi) { const cvt_f32x2 v = {lo, hi}; const cvt_bf16x2 r = __builtin_convertvector(v, cvt_bf16x2); return __builtin_bit_cast(unsigned, r); }
; template <int MAP>
; __device__ __forceinline__ void tr_item(const float* __restrict__ W, int K, int N, const float* __restrict__ gain, bf16_t* WT, LAS float* scr, int item, int lane) {
;     ...
; #pragma unroll
;     for (int i = 0; i < 32; ++i) { const int kk = 2 * i + (lane >> 5); float x = v[i]; if (gain) x *= gain[k0 + kk]; scr[kk * 33 + (lane & 31)] = x; }
;     asm volatile("s_waitcnt lgkmcnt(0)" ::: "memory");
;     const int c = lane & 7;
; #pragma unroll
;     for (int j = 0; j < 4; ++j) {
;         const int nl = (lane >> 3) + 8 * j, n = n0 + nl;
;         const LAS float* s = scr + (8 * c) * 33 + nl;
;         u32x4 o; o.x = cvtpk(s[0 * 33], s[1 * 33]); o.y = cvtpk(s[2 * 33], s[3 * 33]); o.z = cvtpk(s[4 * 33], s[5 * 33]); o.w = cvtpk(s[6 * 33], s[7 * 33]);
;         int dest = n;
;         if (MAP == 1) { if (n >= 3846) dest = n - 6; else if (n >= 3840) dest = C_FF + (n - 3840); }
;         if (n < N) *(u32x4*)(WT + (size_t)dest * K + k0 + 8 * c) = o;
;     }
;     asm volatile("s_waitcnt lgkmcnt(0)" ::: "memory");
.LBB0_1484:
	s_waitcnt vmcnt(7)
	v_add_u32_e32 v0, 0xc00, v24
	ds_write2_b32 v0, v16, v17 offset0:24 offset1:90
	ds_write2_b32 v0, v18, v19 offset0:156 offset1:222
	s_waitcnt lgkmcnt(0)
	ds_read2_b32 v[20:21], v40 offset0:33 offset1:41
	ds_read2_b32 v[22:23], v40 offset1:8
	ds_read2_b32 v[24:25], v40 offset0:66 offset1:74
	ds_read2_b32 v[26:27], v40 offset0:99 offset1:107
	ds_read2_b32 v[28:29], v40 offset0:132 offset1:140
	ds_read2_b32 v[30:31], v40 offset0:165 offset1:173
	s_waitcnt vmcnt(5)
	ds_read2_b32 v[44:45], v40 offset0:198 offset1:206
	s_waitcnt vmcnt(4)
	ds_read2_b32 v[46:47], v40 offset0:231 offset1:239
	s_lshl_b32 s36, s34, 1
	v_or_b32_e32 v0, s31, v39
	v_lshl_add_u64 v[16:17], v[8:9], 0, s[36:37]
	v_lshlrev_b32_e32 v0, 12, v0
	v_lshl_add_u64 v[18:19], v[16:17], 0, v[0:1]
	v_or_b32_e32 v0, s31, v41
	s_waitcnt vmcnt(3) lgkmcnt(6)
	v_cvt_pk_bf16_f32 v12, v22, v20
	s_waitcnt vmcnt(2) lgkmcnt(4)
	v_cvt_pk_bf16_f32 v13, v24, v26
	s_waitcnt vmcnt(1) lgkmcnt(2)
	v_cvt_pk_bf16_f32 v14, v28, v30
	s_waitcnt vmcnt(0) lgkmcnt(0)
	v_cvt_pk_bf16_f32 v15, v44, v46
	v_lshlrev_b32_e32 v0, 12, v0
	global_store_dwordx4 v[18:19], v[12:15], off sc1
	v_lshl_add_u64 v[18:19], v[16:17], 0, v[0:1]
	v_or_b32_e32 v0, s31, v42
	v_cvt_pk_bf16_f32 v12, v23, v21
	v_cvt_pk_bf16_f32 v13, v25, v27
	v_cvt_pk_bf16_f32 v14, v29, v31
	v_cvt_pk_bf16_f32 v15, v45, v47
	global_store_dwordx4 v[18:19], v[12:15], off sc1
	ds_read2_b32 v[20:21], v40 offset0:49 offset1:57
	ds_read2_b32 v[22:23], v40 offset0:16 offset1:24
	ds_read2_b32 v[24:25], v40 offset0:82 offset1:90
	ds_read2_b32 v[26:27], v40 offset0:115 offset1:123
	ds_read2_b32 v[28:29], v40 offset0:148 offset1:156
	ds_read2_b32 v[30:31], v40 offset0:181 offset1:189
	ds_read2_b32 v[44:45], v40 offset0:214 offset1:222
	ds_read2_b32 v[46:47], v40 offset0:247 offset1:255
	v_lshlrev_b32_e32 v0, 12, v0
	v_lshl_add_u64 v[18:19], v[16:17], 0, v[0:1]
	v_or_b32_e32 v0, s31, v43
	s_waitcnt lgkmcnt(6)
	v_cvt_pk_bf16_f32 v12, v22, v20
	s_waitcnt lgkmcnt(4)
	v_cvt_pk_bf16_f32 v13, v24, v26
	s_waitcnt lgkmcnt(2)
	v_cvt_pk_bf16_f32 v14, v28, v30
	s_waitcnt lgkmcnt(0)
	v_cvt_pk_bf16_f32 v15, v44, v46
	v_lshlrev_b32_e32 v0, 12, v0
	global_store_dwordx4 v[18:19], v[12:15], off sc1
	v_lshl_add_u64 v[16:17], v[16:17], 0, v[0:1]
	s_nop 0
	v_cvt_pk_bf16_f32 v12, v23, v21
	v_cvt_pk_bf16_f32 v13, v25, v27
	v_cvt_pk_bf16_f32 v14, v29, v31
	v_cvt_pk_bf16_f32 v15, v45, v47
	global_store_dwordx4 v[16:17], v[12:15], off sc1
	s_waitcnt lgkmcnt(0)

; template <int MAP>
; __device__ __forceinline__ void tr_item(const float* __restrict__ W, int K, int N, const float* __restrict__ gain, bf16_t* WT, LAS float* scr, int item, int lane) {
;     const int nblk = (N + 31) / 32, kb = item / nblk, nb = item % nblk, k0 = 64 * kb, n0 = 32 * nb;
;     const int nsrc = n0 + (lane & 31); const bool ok = nsrc < N;
;     float v[32];
; #pragma unroll
;     for (int i = 0; i < 32; ++i) { const int kk = 2 * i + (lane >> 5); v[i] = ok ? __builtin_nontemporal_load(W + (size_t)(k0 + kk) * N + nsrc) : 0.f; }
; #pragma unroll
;     for (int i = 0; i < 32; ++i) { const int kk = 2 * i + (lane >> 5); float x = v[i]; if (gain) x *= gain[k0 + kk]; scr[kk * 33 + (lane & 31)] = x; }
; __device__ __forceinline__ void tr_dispatch(ArgsP a, int l, int r, LAS float* scr, int lane) {
;     ...
;     if (r < TR_IT_IN) { tr_item<1>(a->in[I_W_IN] + (size_t)l * DM * NIN, DM, NIN, a->in[I_NORM_MIX] + l * DM, (bf16_t*)(ws + WS_WIN + l * SZ_WIN), scr, r, lane); return; } r -= TR_IT_IN;
;     if (r < TR_IT_OUT) { tr_item<0>(a->in[I_WOUT] + (size_t)l * DM * DM, DM, DM, nullptr, (bf16_t*)(ws + WS_WOUT + l * SZ_WOUT), scr, r, lane); return; } r -= TR_IT_OUT;
;     if (r < TR_IT_UP) { tr_item<0>(a->in[I_WUP] + (size_t)l * DM * DFF, DM, DFF, a->in[I_NORM_FFN] + l * DM, (bf16_t*)(ws + WS_WUP + l * SZ_WUP), scr, r, lane); return; } r -= TR_IT_UP;
;     if (r < TR_IT_DN) { tr_item<0>(a->in[I_WDN] + (size_t)l * DFF * DM, DFF, DM, nullptr, (bf16_t*)(ws + WS_WDN + l * SZ_WDN), scr, r, lane); return; } r -= TR_IT_DN;
.LBB0_1486:
	s_andn2_b64 vcc, exec, s[4:5]
	s_cbranch_vccnz .LBB0_1488
	s_load_dwordx2 s[4:5], s[0:1], 0x98
	s_mov_b32 s2, 0x74000
	s_waitcnt lgkmcnt(0)
	s_add_u32 s6, s4, s12
	s_addc_u32 s7, s5, s13
	s_and_b32 s4, s29, 0x7e0
	s_and_b32 s5, s19, 0xffc0
	v_or_b32_e32 v0, s4, v32
	v_or_b32_e32 v14, s5, v2
	v_lshlrev_b32_e32 v0, 2, v0
	v_lshl_add_u64 v[12:13], s[6:7], 0, v[0:1]
	v_lshlrev_b32_e32 v0, 13, v14
	v_lshl_add_u64 v[12:13], v[12:13], 0, v[0:1]
	v_add_co_u32_e32 v14, vcc, s86, v12
	global_load_dword v0, v[12:13], off nt
	s_nop 0
	v_addc_co_u32_e32 v15, vcc, 0, v13, vcc
	global_load_dword v16, v[14:15], off nt
	v_add_co_u32_e32 v14, vcc, s74, v12
	s_lshl_b32 s36, s5, 1
	s_nop 0
	v_addc_co_u32_e32 v15, vcc, 0, v13, vcc
	global_load_dword v17, v[14:15], off nt
	v_add_co_u32_e32 v14, vcc, s78, v12
	s_nop 1
	v_addc_co_u32_e32 v15, vcc, 0, v13, vcc
	global_load_dword v18, v[14:15], off nt
	v_add_co_u32_e32 v14, vcc, s17, v12
	s_nop 1
	v_addc_co_u32_e32 v15, vcc, 0, v13, vcc
	global_load_dword v19, v[14:15], off nt
	v_add_co_u32_e32 v14, vcc, s24, v12
	s_nop 1
	v_addc_co_u32_e32 v15, vcc, 0, v13, vcc
	global_load_dword v20, v[14:15], off nt
	v_add_co_u32_e32 v14, vcc, s87, v12
	s_nop 1
	v_addc_co_u32_e32 v15, vcc, 0, v13, vcc
	global_load_dword v21, v[14:15], off nt
	v_add_co_u32_e32 v14, vcc, s69, v12
	s_nop 1
	v_addc_co_u32_e32 v15, vcc, 0, v13, vcc
	global_load_dword v22, v[14:15], off nt
	v_add_co_u32_e32 v14, vcc, s70, v12
	s_nop 1
	v_addc_co_u32_e32 v15, vcc, 0, v13, vcc
	global_load_dword v23, v[14:15], off nt
	v_add_co_u32_e32 v14, vcc, s72, v12
	s_nop 1
	v_addc_co_u32_e32 v15, vcc, 0, v13, vcc
	global_load_dword v24, v[14:15], off nt
	v_add_co_u32_e32 v14, vcc, s33, v12
	s_nop 1
	v_addc_co_u32_e32 v15, vcc, 0, v13, vcc
	global_load_dword v25, v[14:15], off nt
	v_add_co_u32_e32 v14, vcc, s60, v12
	s_nop 1
	v_addc_co_u32_e32 v15, vcc, 0, v13, vcc
	global_load_dword v26, v[14:15], off nt
	v_add_co_u32_e32 v14, vcc, s83, v12
	s_nop 1
	v_addc_co_u32_e32 v15, vcc, 0, v13, vcc
	global_load_dword v27, v[14:15], off nt
	v_add_co_u32_e32 v14, vcc, s35, v12
	s_nop 1
	v_addc_co_u32_e32 v15, vcc, 0, v13, vcc
	global_load_dword v28, v[14:15], off nt
	v_add_co_u32_e32 v14, vcc, s38, v12
	s_nop 1
	v_addc_co_u32_e32 v15, vcc, 0, v13, vcc
	global_load_dword v29, v[14:15], off nt
	v_add_co_u32_e32 v14, vcc, s39, v12
	s_nop 1
	v_addc_co_u32_e32 v15, vcc, 0, v13, vcc
	global_load_dword v30, v[14:15], off nt
	v_add_co_u32_e32 v14, vcc, s40, v12
	s_nop 1
	v_addc_co_u32_e32 v15, vcc, 0, v13, vcc
	global_load_dword v31, v[14:15], off nt
	v_add_co_u32_e32 v14, vcc, s41, v12
	s_nop 1
	v_addc_co_u32_e32 v15, vcc, 0, v13, vcc
	global_load_dword v44, v[14:15], off nt
	v_add_co_u32_e32 v14, vcc, s42, v12
	s_nop 1
	v_addc_co_u32_e32 v15, vcc, 0, v13, vcc
	global_load_dword v45, v[14:15], off nt
	v_add_co_u32_e32 v14, vcc, s43, v12
	s_nop 1
	v_addc_co_u32_e32 v15, vcc, 0, v13, vcc
	global_load_dword v46, v[14:15], off nt
	v_add_co_u32_e32 v14, vcc, s44, v12
	s_nop 1
	v_addc_co_u32_e32 v15, vcc, 0, v13, vcc
	global_load_dword v47, v[14:15], off nt
	v_add_co_u32_e32 v14, vcc, s45, v12
	s_nop 1
	v_addc_co_u32_e32 v15, vcc, 0, v13, vcc
	global_load_dword v48, v[14:15], off nt
	v_add_co_u32_e32 v14, vcc, s46, v12
	s_nop 1
	v_addc_co_u32_e32 v15, vcc, 0, v13, vcc
	global_load_dword v49, v[14:15], off nt
	v_add_co_u32_e32 v14, vcc, s47, v12
	s_nop 1
	v_addc_co_u32_e32 v15, vcc, 0, v13, vcc
	global_load_dword v50, v[14:15], off nt
	v_add_co_u32_e32 v14, vcc, s68, v12
	s_nop 1
	v_addc_co_u32_e32 v15, vcc, 0, v13, vcc
	global_load_dword v51, v[14:15], off nt
	v_add_co_u32_e32 v14, vcc, s48, v12
	s_nop 1
	v_addc_co_u32_e32 v15, vcc, 0, v13, vcc
	global_load_dword v52, v[14:15], off nt
	v_add_co_u32_e32 v14, vcc, s49, v12
	s_nop 1
	v_addc_co_u32_e32 v15, vcc, 0, v13, vcc
	global_load_dword v53, v[14:15], off nt
	v_add_co_u32_e32 v14, vcc, s91, v12
	s_nop 1
	v_addc_co_u32_e32 v15, vcc, 0, v13, vcc
	global_load_dword v54, v[14:15], off nt
	v_add_co_u32_e32 v14, vcc, s56, v12
	s_nop 1
	v_addc_co_u32_e32 v15, vcc, 0, v13, vcc
	global_load_dword v55, v[14:15], off nt
	v_add_co_u32_e32 v14, vcc, s2, v12
	s_mov_b32 s2, 0x78000
	s_nop 0
	v_addc_co_u32_e32 v15, vcc, 0, v13, vcc
	global_load_dword v56, v[14:15], off nt
	v_add_co_u32_e32 v14, vcc, s2, v12
	s_mov_b32 s2, 0x7c000
	s_nop 0
	v_addc_co_u32_e32 v15, vcc, 0, v13, vcc
	v_add_co_u32_e32 v12, vcc, s2, v12
	global_load_dword v14, v[14:15], off nt
	s_nop 0
	v_addc_co_u32_e32 v13, vcc, 0, v13, vcc
	global_load_dword v12, v[12:13], off nt
	v_add_u32_e32 v13, v33, v34
	s_waitcnt vmcnt(30)
; #define LAS __attribute__((address_space(3)))
; __device__ __forceinline__ unsigned cvtpk(float lo, float hi) { const cvt_f32x2 v = {lo, hi}; const cvt_bf16x2 r = __builtin_convertvector(v, cvt_bf16x2); return __builtin_bit_cast(unsigned, r); }
; template <int MAP>
; __device__ __forceinline__ void tr_item(const float* __restrict__ W, int K, int N, const float* __restrict__ gain, bf16_t* WT, LAS float* scr, int item, int lane) {
;     ...
; #pragma unroll
;     for (int i = 0; i < 32; ++i) { const int kk = 2 * i + (lane >> 5); float x = v[i]; if (gain) x *= gain[k0 + kk]; scr[kk * 33 + (lane & 31)] = x; }
;     asm volatile("s_waitcnt lgkmcnt(0)" ::: "memory");
;     const int c = lane & 7;
; #pragma unroll
;     for (int j = 0; j < 4; ++j) {
;         const int nl = (lane >> 3) + 8 * j, n = n0 + nl;
;         const LAS float* s = scr + (8 * c) * 33 + nl;
;         u32x4 o; o.x = cvtpk(s[0 * 33], s[1 * 33]); o.y = cvtpk(s[2 * 33], s[3 * 33]); o.z = cvtpk(s[4 * 33], s[5 * 33]); o.w = cvtpk(s[6 * 33], s[7 * 33]);
;         int dest = n;
;         if (MAP == 1) { if (n >= 3846) dest = n - 6; else if (n >= 3840) dest = C_FF + (n - 3840); }
;         if (n < N) *(u32x4*)(WT + (size_t)dest * K + k0 + 8 * c) = o;
;     }
;     asm volatile("s_waitcnt lgkmcnt(0)" ::: "memory");
	ds_write2_b32 v13, v0, v16 offset1:66
	s_waitcnt vmcnt(28)
	ds_write2_b32 v13, v17, v18 offset0:132 offset1:198
	v_add_u32_e32 v0, 0x400, v13
	s_waitcnt vmcnt(26)
	ds_write2_b32 v0, v19, v20 offset0:8 offset1:74
	s_waitcnt vmcnt(24)
	ds_write2_b32 v0, v21, v22 offset0:140 offset1:206
	v_add_u32_e32 v0, 0x800, v13
	s_waitcnt vmcnt(22)
	ds_write2_b32 v0, v23, v24 offset0:16 offset1:82
	s_waitcnt vmcnt(20)
	ds_write2_b32 v0, v25, v26 offset0:148 offset1:214
	v_add_u32_e32 v0, 0xc00, v13
	s_waitcnt vmcnt(18)
	ds_write2_b32 v0, v27, v28 offset0:24 offset1:90
	s_waitcnt vmcnt(16)
	ds_write2_b32 v0, v29, v30 offset0:156 offset1:222
	v_add_u32_e32 v0, 0x1000, v13
	s_waitcnt vmcnt(14)
	ds_write2_b32 v0, v31, v44 offset0:32 offset1:98
	s_waitcnt vmcnt(12)
	ds_write2_b32 v0, v45, v46 offset0:164 offset1:230
	v_add_u32_e32 v0, 0x1400, v13
	s_waitcnt vmcnt(10)
	ds_write2_b32 v0, v47, v48 offset0:40 offset1:106
	s_waitcnt vmcnt(8)
	ds_write2_b32 v0, v49, v50 offset0:172 offset1:238
	v_add_u32_e32 v0, 0x1800, v13
	s_waitcnt vmcnt(6)
	ds_write2_b32 v0, v51, v52 offset0:48 offset1:114
	s_waitcnt vmcnt(4)
	ds_write2_b32 v0, v53, v54 offset0:180 offset1:246
	v_add_u32_e32 v0, 0x1c00, v13
	s_waitcnt vmcnt(2)
	ds_write2_b32 v0, v55, v56 offset0:56 offset1:122
	s_waitcnt vmcnt(0)
	ds_write2_b32 v0, v14, v12 offset0:188 offset1:254
	s_waitcnt lgkmcnt(0)
	ds_read2_b32 v[20:21], v40 offset0:33 offset1:41
	ds_read2_b32 v[22:23], v40 offset1:8
	ds_read2_b32 v[24:25], v40 offset0:66 offset1:74
	ds_read2_b32 v[26:27], v40 offset0:99 offset1:107
	ds_read2_b32 v[28:29], v40 offset0:132 offset1:140
	ds_read2_b32 v[30:31], v40 offset0:165 offset1:173
	ds_read2_b32 v[44:45], v40 offset0:198 offset1:206
	ds_read2_b32 v[46:47], v40 offset0:231 offset1:239
	v_or_b32_e32 v0, s4, v39
	v_lshl_add_u64 v[16:17], v[10:11], 0, s[36:37]
	v_lshlrev_b32_e32 v0, 12, v0
	v_lshl_add_u64 v[18:19], v[16:17], 0, v[0:1]
	v_or_b32_e32 v0, s4, v41
	s_waitcnt lgkmcnt(6)
	v_cvt_pk_bf16_f32 v12, v22, v20
	s_waitcnt lgkmcnt(4)
	v_cvt_pk_bf16_f32 v13, v24, v26
	s_waitcnt lgkmcnt(2)
	v_cvt_pk_bf16_f32 v14, v28, v30
	s_waitcnt lgkmcnt(0)
	v_cvt_pk_bf16_f32 v15, v44, v46
	v_lshlrev_b32_e32 v0, 12, v0
	global_store_dwordx4 v[18:19], v[12:15], off sc1
	v_lshl_add_u64 v[18:19], v[16:17], 0, v[0:1]
	v_or_b32_e32 v0, s4, v42
	v_cvt_pk_bf16_f32 v12, v23, v21
	v_cvt_pk_bf16_f32 v13, v25, v27
	v_cvt_pk_bf16_f32 v14, v29, v31
	v_cvt_pk_bf16_f32 v15, v45, v47
	global_store_dwordx4 v[18:19], v[12:15], off sc1
	ds_read2_b32 v[20:21], v40 offset0:49 offset1:57
	ds_read2_b32 v[22:23], v40 offset0:16 offset1:24
	ds_read2_b32 v[24:25], v40 offset0:82 offset1:90
	ds_read2_b32 v[26:27], v40 offset0:115 offset1:123
	ds_read2_b32 v[28:29], v40 offset0:148 offset1:156
	ds_read2_b32 v[30:31], v40 offset0:181 offset1:189
	ds_read2_b32 v[44:45], v40 offset0:214 offset1:222
	ds_read2_b32 v[46:47], v40 offset0:247 offset1:255
	v_lshlrev_b32_e32 v0, 12, v0
	v_lshl_add_u64 v[18:19], v[16:17], 0, v[0:1]
	v_or_b32_e32 v0, s4, v43
	s_waitcnt lgkmcnt(6)
	v_cvt_pk_bf16_f32 v12, v22, v20
	s_waitcnt lgkmcnt(4)
	v_cvt_pk_bf16_f32 v13, v24, v26
	s_waitcnt lgkmcnt(2)
	v_cvt_pk_bf16_f32 v14, v28, v30
	s_waitcnt lgkmcnt(0)
	v_cvt_pk_bf16_f32 v15, v44, v46
	v_lshlrev_b32_e32 v0, 12, v0
	global_store_dwordx4 v[18:19], v[12:15], off sc1
	v_lshl_add_u64 v[16:17], v[16:17], 0, v[0:1]
	s_nop 0
	v_cvt_pk_bf16_f32 v12, v23, v21
	v_cvt_pk_bf16_f32 v13, v25, v27
	v_cvt_pk_bf16_f32 v14, v29, v31
	v_cvt_pk_bf16_f32 v15, v45, v47
	global_store_dwordx4 v[16:17], v[12:15], off sc1
	s_waitcnt lgkmcnt(0)

; #define LAS __attribute__((address_space(3)))
; __device__ __forceinline__ unsigned cvtpk(float lo, float hi) { const cvt_f32x2 v = {lo, hi}; const cvt_bf16x2 r = __builtin_convertvector(v, cvt_bf16x2); return __builtin_bit_cast(unsigned, r); }
; template <int MAP>
; __device__ __forceinline__ void tr_item(const float* __restrict__ W, int K, int N, const float* __restrict__ gain, bf16_t* WT, LAS float* scr, int item, int lane) {
;     ...
;     const int c = lane & 7;
; #pragma unroll
;     for (int j = 0; j < 4; ++j) {
;         const int nl = (lane >> 3) + 8 * j, n = n0 + nl;
;         const LAS float* s = scr + (8 * c) * 33 + nl;
;         u32x4 o; o.x = cvtpk(s[0 * 33], s[1 * 33]); o.y = cvtpk(s[2 * 33], s[3 * 33]); o.z = cvtpk(s[4 * 33], s[5 * 33]); o.w = cvtpk(s[6 * 33], s[7 * 33]);
;         int dest = n;
;         if (MAP == 1) { if (n >= 3846) dest = n - 6; else if (n >= 3840) dest = C_FF + (n - 3840); }
;         if (n < N) *(u32x4*)(WT + (size_t)dest * K + k0 + 8 * c) = o;
;     }
;     asm volatile("s_waitcnt lgkmcnt(0)" ::: "memory");
.LBB0_1566:
	v_add_u32_e32 v0, 0xc00, v24
	ds_write2_b32 v0, v16, v17 offset0:24 offset1:90
	ds_write2_b32 v0, v18, v19 offset0:156 offset1:222
	s_waitcnt lgkmcnt(0)
	v_or_b32_e32 v0, s31, v39
	v_lshl_add_u64 v[12:13], s[6:7], 1, v[4:5]
	v_cmp_gt_i32_e32 vcc, s71, v0
	s_and_saveexec_b64 s[4:5], vcc
	s_cbranch_execz .LBB0_1568
	v_add_u32_e32 v15, 0x340, v0
	v_cmp_lt_i32_e32 vcc, s55, v0
	ds_read2_b32 v[16:17], v40 offset1:33
	ds_read2_b32 v[18:19], v40 offset0:66 offset1:99
	ds_read2_b32 v[20:21], v40 offset0:132 offset1:165
	ds_read2_b32 v[22:23], v40 offset0:198 offset1:231
	v_add_u32_e32 v14, -6, v0
	v_cndmask_b32_e32 v15, v0, v15, vcc
	v_cmp_lt_i32_e32 vcc, s25, v0
	s_nop 1
	v_cndmask_b32_e32 v14, v15, v14, vcc
	v_ashrrev_i32_e32 v15, 31, v14
	v_lshlrev_b64 v[14:15], 12, v[14:15]
	v_lshl_add_u64 v[24:25], v[12:13], 0, v[14:15]
	s_waitcnt lgkmcnt(3)
	v_cvt_pk_bf16_f32 v14, v16, v17
	s_waitcnt lgkmcnt(2)
	v_cvt_pk_bf16_f32 v15, v18, v19
	s_waitcnt lgkmcnt(1)
	v_cvt_pk_bf16_f32 v16, v20, v21
	s_waitcnt lgkmcnt(0)
	v_cvt_pk_bf16_f32 v17, v22, v23
	global_store_dwordx4 v[24:25], v[14:17], off sc1
.LBB0_1568:
	s_or_b64 exec, exec, s[4:5]
	v_or_b32_e32 v0, s31, v41
	v_cmp_gt_i32_e32 vcc, s71, v0
	s_and_saveexec_b64 s[4:5], vcc
	s_cbranch_execz .LBB0_1570
	v_add_u32_e32 v15, 0x340, v0
	v_cmp_lt_i32_e32 vcc, s55, v0
	ds_read2_b32 v[16:17], v40 offset0:8 offset1:41
	ds_read2_b32 v[18:19], v40 offset0:74 offset1:107
	ds_read2_b32 v[20:21], v40 offset0:140 offset1:173
	ds_read2_b32 v[22:23], v40 offset0:206 offset1:239
	v_add_u32_e32 v14, -6, v0
	v_cndmask_b32_e32 v15, v0, v15, vcc
	v_cmp_lt_i32_e32 vcc, s25, v0
	s_nop 1
	v_cndmask_b32_e32 v14, v15, v14, vcc
	v_ashrrev_i32_e32 v15, 31, v14
	v_lshlrev_b64 v[14:15], 12, v[14:15]
	v_lshl_add_u64 v[24:25], v[12:13], 0, v[14:15]
	s_waitcnt lgkmcnt(3)
	v_cvt_pk_bf16_f32 v14, v16, v17
	s_waitcnt lgkmcnt(2)
	v_cvt_pk_bf16_f32 v15, v18, v19
	s_waitcnt lgkmcnt(1)
	v_cvt_pk_bf16_f32 v16, v20, v21
	s_waitcnt lgkmcnt(0)
	v_cvt_pk_bf16_f32 v17, v22, v23
	global_store_dwordx4 v[24:25], v[14:17], off sc1
.LBB0_1570:
	s_or_b64 exec, exec, s[4:5]
	v_or_b32_e32 v0, s31, v42
	v_cmp_gt_i32_e32 vcc, s71, v0
	s_and_saveexec_b64 s[4:5], vcc
	s_cbranch_execz .LBB0_1572
	v_add_u32_e32 v15, 0x340, v0
	v_cmp_lt_i32_e32 vcc, s55, v0
	ds_read2_b32 v[16:17], v40 offset0:16 offset1:49
	ds_read2_b32 v[18:19], v40 offset0:82 offset1:115
	ds_read2_b32 v[20:21], v40 offset0:148 offset1:181
	ds_read2_b32 v[22:23], v40 offset0:214 offset1:247
	v_add_u32_e32 v14, -6, v0
	v_cndmask_b32_e32 v15, v0, v15, vcc
	v_cmp_lt_i32_e32 vcc, s25, v0
	s_nop 1
	v_cndmask_b32_e32 v14, v15, v14, vcc
	v_ashrrev_i32_e32 v15, 31, v14
	v_lshlrev_b64 v[14:15], 12, v[14:15]
	v_lshl_add_u64 v[24:25], v[12:13], 0, v[14:15]
	s_waitcnt lgkmcnt(3)
	v_cvt_pk_bf16_f32 v14, v16, v17
	s_waitcnt lgkmcnt(2)
	v_cvt_pk_bf16_f32 v15, v18, v19
	s_waitcnt lgkmcnt(1)
	v_cvt_pk_bf16_f32 v16, v20, v21
	s_waitcnt lgkmcnt(0)
	v_cvt_pk_bf16_f32 v17, v22, v23
	global_store_dwordx4 v[24:25], v[14:17], off sc1
.LBB0_1572:
	s_or_b64 exec, exec, s[4:5]
	v_or_b32_e32 v0, s31, v43
	v_cmp_gt_i32_e32 vcc, s71, v0
	s_and_saveexec_b64 s[4:5], vcc
	s_cbranch_execz .LBB0_1464
	v_add_u32_e32 v15, 0x340, v0
	v_cmp_lt_i32_e32 vcc, s55, v0
	ds_read2_b32 v[16:17], v40 offset0:24 offset1:57
	ds_read2_b32 v[18:19], v40 offset0:90 offset1:123
	ds_read2_b32 v[20:21], v40 offset0:156 offset1:189
	ds_read2_b32 v[22:23], v40 offset0:222 offset1:255
	v_add_u32_e32 v14, -6, v0
	v_cndmask_b32_e32 v15, v0, v15, vcc
	v_cmp_lt_i32_e32 vcc, s25, v0
	s_nop 1
	v_cndmask_b32_e32 v14, v15, v14, vcc
	v_ashrrev_i32_e32 v15, 31, v14
	v_lshlrev_b64 v[14:15], 12, v[14:15]
	v_lshl_add_u64 v[24:25], v[12:13], 0, v[14:15]
	s_waitcnt lgkmcnt(3)
	v_cvt_pk_bf16_f32 v12, v16, v17
	s_waitcnt lgkmcnt(2)
	v_cvt_pk_bf16_f32 v13, v18, v19
	s_waitcnt lgkmcnt(1)
	v_cvt_pk_bf16_f32 v14, v20, v21
	s_waitcnt lgkmcnt(0)
	v_cvt_pk_bf16_f32 v15, v22, v23
	global_store_dwordx4 v[24:25], v[12:15], off sc1
	s_branch .LBB0_1464
